# attention epilogue: first four butterfly rounds of the row reduction via DPP adds instead of ds_bpermute round trips
# baseline (speedup 1.0000x reference)
.LBB0_303:
	s_cmpk_gt_u32 s65, 0xff
	s_waitcnt lgkmcnt(0)
	s_barrier
	s_cbranch_scc1 .LBB0_275
	s_mulk_i32 s64, 0x2200
	s_add_i32 s34, s64, 0
	s_add_i32 s34, s34, 0x10000
	ds_read2st64_b32 v[130:131], v71 offset1:1
	ds_read2st64_b32 v[132:133], v71 offset0:2 offset1:3
	ds_read2st64_b32 v[134:135], v71 offset0:4 offset1:5
	ds_read2st64_b32 v[136:137], v71 offset0:6 offset1:7
	ds_read2st64_b32 v[138:139], v71 offset0:8 offset1:9
	ds_read2st64_b32 v[140:141], v71 offset0:10 offset1:11
	ds_read2st64_b32 v[142:143], v71 offset0:12 offset1:13
	ds_read2st64_b32 v[144:145], v71 offset0:14 offset1:15
	ds_read2st64_b32 v[146:147], v71 offset0:16 offset1:17
	ds_read2st64_b32 v[148:149], v71 offset0:18 offset1:19
	ds_read2st64_b32 v[150:151], v71 offset0:20 offset1:21
	ds_read2st64_b32 v[172:173], v71 offset0:22 offset1:23
	ds_read2st64_b32 v[174:175], v71 offset0:24 offset1:25
	ds_read2st64_b32 v[176:177], v71 offset0:26 offset1:27
	ds_read2st64_b32 v[178:179], v71 offset0:28 offset1:29
	ds_read2st64_b32 v[180:181], v71 offset0:30 offset1:31
	ds_read2st64_b32 v[182:183], v71 offset0:32 offset1:33
	ds_read2st64_b32 v[184:185], v71 offset0:34 offset1:35
	ds_read2st64_b32 v[186:187], v71 offset0:36 offset1:37
	ds_read2st64_b32 v[188:189], v71 offset0:38 offset1:39
	ds_read2st64_b32 v[190:191], v71 offset0:40 offset1:41
	ds_read2st64_b32 v[192:193], v71 offset0:42 offset1:43
	ds_read2st64_b32 v[194:195], v71 offset0:44 offset1:45
	ds_read2st64_b32 v[196:197], v71 offset0:46 offset1:47
	ds_read2st64_b32 v[198:199], v71 offset0:48 offset1:49
	ds_read2st64_b32 v[200:201], v71 offset0:50 offset1:51
	ds_read2st64_b32 v[202:203], v71 offset0:52 offset1:53
	ds_read2st64_b32 v[204:205], v71 offset0:54 offset1:55
	ds_read2st64_b32 v[206:207], v71 offset0:56 offset1:57
	ds_read2st64_b32 v[208:209], v71 offset0:58 offset1:59
	ds_read2st64_b32 v[210:211], v71 offset0:60 offset1:61
	ds_read2st64_b32 v[212:213], v71 offset0:62 offset1:63
	s_waitcnt lgkmcnt(15)
	v_sub_f32_e32 v60, v72, v130
	v_sub_f32_e32 v55, v0, v131
	v_sub_f32_e32 v52, v73, v132
	v_sub_f32_e32 v47, v74, v133
	v_sub_f32_e32 v44, v3, v134
	v_sub_f32_e32 v39, v36, v135
	v_sub_f32_e32 v28, v23, v138
	v_sub_f32_e32 v23, v38, v139
	v_sub_f32_e32 v36, v20, v136
	v_sub_f32_e32 v31, v6, v137
	v_sub_f32_e32 v20, v41, v140
	v_sub_f32_e32 v15, v26, v141
	v_sub_f32_e32 v12, v54, v142
	v_sub_f32_e32 v6, v77, v143
	v_sub_f32_e32 v3, v57, v144
	v_sub_f32_e32 v0, v14, v145
	v_sub_f32_e32 v62, v68, v146
	v_sub_f32_e32 v57, v49, v147
	v_sub_f32_e32 v54, v1, v148
	v_sub_f32_e32 v49, v18, v149
	v_sub_f32_e32 v46, v34, v150
	v_sub_f32_e32 v41, v51, v151
	v_sub_f32_e32 v38, v5, v172
	v_sub_f32_e32 v34, v22, v173
	v_sub_f32_e32 v30, v40, v174
	v_sub_f32_e32 v26, v56, v175
	v_sub_f32_e32 v22, v75, v176
	v_sub_f32_e32 v18, v10, v177
	v_sub_f32_e32 v14, v27, v178
	v_sub_f32_e32 v10, v59, v179
	v_sub_f32_e32 v5, v43, v180
	v_sub_f32_e32 v1, v76, v181
	v_sub_f32_e32 v74, v16, v182
	v_sub_f32_e32 v59, v32, v183
	s_waitcnt lgkmcnt(14)
	v_sub_f32_e32 v56, v48, v184
	v_sub_f32_e32 v51, v2, v185
	s_waitcnt lgkmcnt(13)
	v_sub_f32_e32 v48, v19, v186
	v_sub_f32_e32 v43, v53, v187
	s_waitcnt lgkmcnt(12)
	v_sub_f32_e32 v40, v35, v188
	v_sub_f32_e32 v35, v69, v189
	s_waitcnt lgkmcnt(11)
	v_sub_f32_e32 v32, v7, v190
	v_sub_f32_e32 v27, v24, v191
	s_waitcnt lgkmcnt(10)
	v_sub_f32_e32 v24, v42, v192
	v_sub_f32_e32 v19, v58, v193
	s_waitcnt lgkmcnt(9)
	v_sub_f32_e32 v16, v11, v194
	v_sub_f32_e32 v11, v29, v195
	s_waitcnt lgkmcnt(8)
	v_sub_f32_e32 v7, v45, v196
	v_sub_f32_e32 v2, v61, v197
	s_waitcnt lgkmcnt(7)
	v_sub_f32_e32 v72, v64, v198
	v_sub_f32_e32 v61, v17, v199
	s_waitcnt lgkmcnt(6)
	v_sub_f32_e32 v58, v33, v200
	v_sub_f32_e32 v53, v50, v201
	s_waitcnt lgkmcnt(5)
	v_sub_f32_e32 v50, v4, v202
	v_sub_f32_e32 v45, v21, v203
	s_waitcnt lgkmcnt(4)
	v_sub_f32_e32 v42, v37, v204
	v_sub_f32_e32 v37, v65, v205
	s_waitcnt lgkmcnt(3)
	v_sub_f32_e32 v33, v8, v206
	v_sub_f32_e32 v29, v9, v207
	s_waitcnt lgkmcnt(2)
	v_sub_f32_e32 v25, v25, v208
	v_sub_f32_e32 v21, v66, v209
	s_waitcnt lgkmcnt(0)
	v_sub_f32_e32 v4, v63, v213
	v_sub_f32_e32 v13, v13, v211
	v_sub_f32_e32 v9, v70, v212
	v_sub_f32_e32 v17, v67, v210
	s_waitcnt lgkmcnt(0)
	v_mul_f32_e32 v130, v62, v62
	v_fmac_f32_e32 v130, v60, v60
	v_fmac_f32_e32 v130, v74, v74
	v_fmac_f32_e32 v130, v72, v72
	v_mul_f32_e32 v131, v57, v57
	v_fmac_f32_e32 v131, v55, v55
	v_fmac_f32_e32 v131, v59, v59
	v_fmac_f32_e32 v131, v61, v61
	v_mul_f32_e32 v132, v54, v54
	v_fmac_f32_e32 v132, v52, v52
	v_fmac_f32_e32 v132, v56, v56
	v_fmac_f32_e32 v132, v58, v58
	v_mul_f32_e32 v133, v49, v49
	v_fmac_f32_e32 v133, v47, v47
	v_fmac_f32_e32 v133, v51, v51
	v_fmac_f32_e32 v133, v53, v53
	v_mul_f32_e32 v134, v46, v46
	v_fmac_f32_e32 v134, v44, v44
	v_fmac_f32_e32 v134, v48, v48
	v_fmac_f32_e32 v134, v50, v50
	v_mul_f32_e32 v135, v41, v41
	v_fmac_f32_e32 v135, v39, v39
	v_fmac_f32_e32 v135, v43, v43
	v_fmac_f32_e32 v135, v45, v45
	v_mul_f32_e32 v136, v38, v38
	v_fmac_f32_e32 v136, v36, v36
	v_fmac_f32_e32 v136, v40, v40
	v_fmac_f32_e32 v136, v42, v42
	v_mul_f32_e32 v137, v34, v34
	v_fmac_f32_e32 v137, v31, v31
	v_fmac_f32_e32 v137, v35, v35
	v_fmac_f32_e32 v137, v37, v37
	v_mul_f32_e32 v138, v30, v30
	v_fmac_f32_e32 v138, v28, v28
	v_fmac_f32_e32 v138, v32, v32
	v_fmac_f32_e32 v138, v33, v33
	v_mul_f32_e32 v139, v26, v26
	v_fmac_f32_e32 v139, v23, v23
	v_fmac_f32_e32 v139, v27, v27
	v_fmac_f32_e32 v139, v29, v29
	v_mul_f32_e32 v140, v22, v22
	v_fmac_f32_e32 v140, v20, v20
	v_fmac_f32_e32 v140, v24, v24
	v_fmac_f32_e32 v140, v25, v25
	v_mul_f32_e32 v141, v18, v18
	v_fmac_f32_e32 v141, v15, v15
	v_fmac_f32_e32 v141, v19, v19
	v_fmac_f32_e32 v141, v21, v21
	v_mul_f32_e32 v142, v14, v14
	v_fmac_f32_e32 v142, v12, v12
	v_fmac_f32_e32 v142, v16, v16
	v_fmac_f32_e32 v142, v17, v17
	v_mul_f32_e32 v143, v10, v10
	v_fmac_f32_e32 v143, v6, v6
	v_fmac_f32_e32 v143, v11, v11
	v_fmac_f32_e32 v143, v13, v13
	v_mul_f32_e32 v144, v5, v5
	v_fmac_f32_e32 v144, v3, v3
	v_fmac_f32_e32 v144, v7, v7
	v_fmac_f32_e32 v144, v9, v9
	v_mul_f32_e32 v145, v1, v1
	v_fmac_f32_e32 v145, v0, v0
	v_fmac_f32_e32 v145, v2, v2
	v_fmac_f32_e32 v145, v4, v4
	v_add_f32_dpp v130, v130, v130 quad_perm:[1,0,3,2] row_mask:0xf bank_mask:0xf
	v_add_f32_dpp v131, v131, v131 quad_perm:[1,0,3,2] row_mask:0xf bank_mask:0xf
	v_add_f32_dpp v132, v132, v132 quad_perm:[1,0,3,2] row_mask:0xf bank_mask:0xf
	v_add_f32_dpp v133, v133, v133 quad_perm:[1,0,3,2] row_mask:0xf bank_mask:0xf
	v_add_f32_dpp v134, v134, v134 quad_perm:[1,0,3,2] row_mask:0xf bank_mask:0xf
	v_add_f32_dpp v135, v135, v135 quad_perm:[1,0,3,2] row_mask:0xf bank_mask:0xf
	v_add_f32_dpp v136, v136, v136 quad_perm:[1,0,3,2] row_mask:0xf bank_mask:0xf
	v_add_f32_dpp v137, v137, v137 quad_perm:[1,0,3,2] row_mask:0xf bank_mask:0xf
	v_add_f32_dpp v138, v138, v138 quad_perm:[1,0,3,2] row_mask:0xf bank_mask:0xf
	v_add_f32_dpp v139, v139, v139 quad_perm:[1,0,3,2] row_mask:0xf bank_mask:0xf
	v_add_f32_dpp v140, v140, v140 quad_perm:[1,0,3,2] row_mask:0xf bank_mask:0xf
	v_add_f32_dpp v141, v141, v141 quad_perm:[1,0,3,2] row_mask:0xf bank_mask:0xf
	v_add_f32_dpp v142, v142, v142 quad_perm:[1,0,3,2] row_mask:0xf bank_mask:0xf
	v_add_f32_dpp v143, v143, v143 quad_perm:[1,0,3,2] row_mask:0xf bank_mask:0xf
	v_add_f32_dpp v144, v144, v144 quad_perm:[1,0,3,2] row_mask:0xf bank_mask:0xf
	v_add_f32_dpp v145, v145, v145 quad_perm:[1,0,3,2] row_mask:0xf bank_mask:0xf
	v_add_f32_dpp v130, v130, v130 quad_perm:[2,3,0,1] row_mask:0xf bank_mask:0xf
	v_add_f32_dpp v131, v131, v131 quad_perm:[2,3,0,1] row_mask:0xf bank_mask:0xf
	v_add_f32_dpp v132, v132, v132 quad_perm:[2,3,0,1] row_mask:0xf bank_mask:0xf
	v_add_f32_dpp v133, v133, v133 quad_perm:[2,3,0,1] row_mask:0xf bank_mask:0xf
	v_add_f32_dpp v134, v134, v134 quad_perm:[2,3,0,1] row_mask:0xf bank_mask:0xf
	v_add_f32_dpp v135, v135, v135 quad_perm:[2,3,0,1] row_mask:0xf bank_mask:0xf
	v_add_f32_dpp v136, v136, v136 quad_perm:[2,3,0,1] row_mask:0xf bank_mask:0xf
	v_add_f32_dpp v137, v137, v137 quad_perm:[2,3,0,1] row_mask:0xf bank_mask:0xf
	v_add_f32_dpp v138, v138, v138 quad_perm:[2,3,0,1] row_mask:0xf bank_mask:0xf
	v_add_f32_dpp v139, v139, v139 quad_perm:[2,3,0,1] row_mask:0xf bank_mask:0xf
	v_add_f32_dpp v140, v140, v140 quad_perm:[2,3,0,1] row_mask:0xf bank_mask:0xf
	v_add_f32_dpp v141, v141, v141 quad_perm:[2,3,0,1] row_mask:0xf bank_mask:0xf
	v_add_f32_dpp v142, v142, v142 quad_perm:[2,3,0,1] row_mask:0xf bank_mask:0xf
	v_add_f32_dpp v143, v143, v143 quad_perm:[2,3,0,1] row_mask:0xf bank_mask:0xf
	v_add_f32_dpp v144, v144, v144 quad_perm:[2,3,0,1] row_mask:0xf bank_mask:0xf
	v_add_f32_dpp v145, v145, v145 quad_perm:[2,3,0,1] row_mask:0xf bank_mask:0xf
	v_add_f32_dpp v130, v130, v130 row_half_mirror row_mask:0xf bank_mask:0xf
	v_add_f32_dpp v131, v131, v131 row_half_mirror row_mask:0xf bank_mask:0xf
	v_add_f32_dpp v132, v132, v132 row_half_mirror row_mask:0xf bank_mask:0xf
	v_add_f32_dpp v133, v133, v133 row_half_mirror row_mask:0xf bank_mask:0xf
	v_add_f32_dpp v134, v134, v134 row_half_mirror row_mask:0xf bank_mask:0xf
	v_add_f32_dpp v135, v135, v135 row_half_mirror row_mask:0xf bank_mask:0xf
	v_add_f32_dpp v136, v136, v136 row_half_mirror row_mask:0xf bank_mask:0xf
	v_add_f32_dpp v137, v137, v137 row_half_mirror row_mask:0xf bank_mask:0xf
	v_add_f32_dpp v138, v138, v138 row_half_mirror row_mask:0xf bank_mask:0xf
	v_add_f32_dpp v139, v139, v139 row_half_mirror row_mask:0xf bank_mask:0xf
	v_add_f32_dpp v140, v140, v140 row_half_mirror row_mask:0xf bank_mask:0xf
	v_add_f32_dpp v141, v141, v141 row_half_mirror row_mask:0xf bank_mask:0xf
	v_add_f32_dpp v142, v142, v142 row_half_mirror row_mask:0xf bank_mask:0xf
	v_add_f32_dpp v143, v143, v143 row_half_mirror row_mask:0xf bank_mask:0xf
	v_add_f32_dpp v144, v144, v144 row_half_mirror row_mask:0xf bank_mask:0xf
	v_add_f32_dpp v145, v145, v145 row_half_mirror row_mask:0xf bank_mask:0xf
	v_add_f32_dpp v130, v130, v130 row_mirror row_mask:0xf bank_mask:0xf
	v_add_f32_dpp v131, v131, v131 row_mirror row_mask:0xf bank_mask:0xf
	v_add_f32_dpp v132, v132, v132 row_mirror row_mask:0xf bank_mask:0xf
	v_add_f32_dpp v133, v133, v133 row_mirror row_mask:0xf bank_mask:0xf
	v_add_f32_dpp v134, v134, v134 row_mirror row_mask:0xf bank_mask:0xf
	v_add_f32_dpp v135, v135, v135 row_mirror row_mask:0xf bank_mask:0xf
	v_add_f32_dpp v136, v136, v136 row_mirror row_mask:0xf bank_mask:0xf
	v_add_f32_dpp v137, v137, v137 row_mirror row_mask:0xf bank_mask:0xf
	v_add_f32_dpp v138, v138, v138 row_mirror row_mask:0xf bank_mask:0xf
	v_add_f32_dpp v139, v139, v139 row_mirror row_mask:0xf bank_mask:0xf
	v_add_f32_dpp v140, v140, v140 row_mirror row_mask:0xf bank_mask:0xf
	v_add_f32_dpp v141, v141, v141 row_mirror row_mask:0xf bank_mask:0xf
	v_add_f32_dpp v142, v142, v142 row_mirror row_mask:0xf bank_mask:0xf
	v_add_f32_dpp v143, v143, v143 row_mirror row_mask:0xf bank_mask:0xf
	v_add_f32_dpp v144, v144, v144 row_mirror row_mask:0xf bank_mask:0xf
	v_add_f32_dpp v145, v145, v145 row_mirror row_mask:0xf bank_mask:0xf
	ds_bpermute_b32 v146, v165, v130
	ds_bpermute_b32 v147, v165, v131
	ds_bpermute_b32 v148, v165, v132
	ds_bpermute_b32 v149, v165, v133
	ds_bpermute_b32 v150, v165, v134
	ds_bpermute_b32 v151, v165, v135
	ds_bpermute_b32 v172, v165, v136
	ds_bpermute_b32 v173, v165, v137
	ds_bpermute_b32 v174, v165, v138
	ds_bpermute_b32 v175, v165, v139
	ds_bpermute_b32 v176, v165, v140
	ds_bpermute_b32 v177, v165, v141
	ds_bpermute_b32 v178, v165, v142
	ds_bpermute_b32 v179, v165, v143
	ds_bpermute_b32 v180, v165, v144
	ds_bpermute_b32 v181, v165, v145
	s_waitcnt lgkmcnt(15)
	v_add_f32_e32 v130, v130, v146
	s_waitcnt lgkmcnt(14)
	v_add_f32_e32 v131, v131, v147
	s_waitcnt lgkmcnt(13)
	v_add_f32_e32 v132, v132, v148
	s_waitcnt lgkmcnt(12)
	v_add_f32_e32 v133, v133, v149
	s_waitcnt lgkmcnt(11)
	v_add_f32_e32 v134, v134, v150
	s_waitcnt lgkmcnt(10)
	v_add_f32_e32 v135, v135, v151
	s_waitcnt lgkmcnt(9)
	v_add_f32_e32 v136, v136, v172
	s_waitcnt lgkmcnt(8)
	v_add_f32_e32 v137, v137, v173
	s_waitcnt lgkmcnt(7)
	v_add_f32_e32 v138, v138, v174
	s_waitcnt lgkmcnt(6)
	v_add_f32_e32 v139, v139, v175
	s_waitcnt lgkmcnt(5)
	v_add_f32_e32 v140, v140, v176
	s_waitcnt lgkmcnt(4)
	v_add_f32_e32 v141, v141, v177
	s_waitcnt lgkmcnt(3)
	v_add_f32_e32 v142, v142, v178
	s_waitcnt lgkmcnt(2)
	v_add_f32_e32 v143, v143, v179
	s_waitcnt lgkmcnt(1)
	v_add_f32_e32 v144, v144, v180
	s_waitcnt lgkmcnt(0)
	v_add_f32_e32 v145, v145, v181
	v_fmamk_f32 v130, v130, 0x3c000000, v153
	v_fmamk_f32 v131, v131, 0x3c000000, v153
	v_fmamk_f32 v132, v132, 0x3c000000, v153
	v_fmamk_f32 v133, v133, 0x3c000000, v153
	v_fmamk_f32 v134, v134, 0x3c000000, v153
	v_fmamk_f32 v135, v135, 0x3c000000, v153
	v_fmamk_f32 v136, v136, 0x3c000000, v153
	v_fmamk_f32 v137, v137, 0x3c000000, v153
	v_fmamk_f32 v138, v138, 0x3c000000, v153
	v_fmamk_f32 v139, v139, 0x3c000000, v153
	v_fmamk_f32 v140, v140, 0x3c000000, v153
	v_fmamk_f32 v141, v141, 0x3c000000, v153
	v_fmamk_f32 v142, v142, 0x3c000000, v153
	v_fmamk_f32 v143, v143, 0x3c000000, v153
	v_fmamk_f32 v144, v144, 0x3c000000, v153
	v_fmamk_f32 v145, v145, 0x3c000000, v153
	v_rsq_f32_e32 v130, v130
	v_rsq_f32_e32 v131, v131
	v_rsq_f32_e32 v132, v132
	v_rsq_f32_e32 v133, v133
	v_rsq_f32_e32 v134, v134
	v_rsq_f32_e32 v135, v135
	v_rsq_f32_e32 v136, v136
	v_rsq_f32_e32 v137, v137
	v_rsq_f32_e32 v138, v138
	v_rsq_f32_e32 v139, v139
	v_rsq_f32_e32 v140, v140
	v_rsq_f32_e32 v141, v141
	v_rsq_f32_e32 v142, v142
	v_rsq_f32_e32 v143, v143
	v_rsq_f32_e32 v144, v144
	v_rsq_f32_e32 v145, v145
	v_lshlrev_b32_e32 v190, 1, v171
	v_mul_u32_u24_e32 v191, 0x440, v170
	v_add3_u32 v190, s34, v190, v191
	v_mul_f32_e32 v182, v60, v130
	v_bfe_u32 v186, v182, 16, 1
	v_add3_u32 v182, v182, v186, s81
	ds_write_b16_d16_hi v190, v182
	v_mul_f32_e32 v183, v62, v130
	v_bfe_u32 v187, v183, 16, 1
	v_add3_u32 v183, v183, v187, s81
	ds_write_b16_d16_hi v190, v183 offset:64
	v_mul_f32_e32 v184, v74, v130
	v_bfe_u32 v188, v184, 16, 1
	v_add3_u32 v184, v184, v188, s81
	ds_write_b16_d16_hi v190, v184 offset:128
	v_mul_f32_e32 v185, v72, v130
	v_bfe_u32 v189, v185, 16, 1
	v_add3_u32 v185, v185, v189, s81
	ds_write_b16_d16_hi v190, v185 offset:192
	v_mul_f32_e32 v182, v55, v131
	v_bfe_u32 v186, v182, 16, 1
	v_add3_u32 v182, v182, v186, s81
	ds_write_b16_d16_hi v190, v182 offset:272
	v_mul_f32_e32 v183, v57, v131
	v_bfe_u32 v187, v183, 16, 1
	v_add3_u32 v183, v183, v187, s81
	ds_write_b16_d16_hi v190, v183 offset:336
	v_mul_f32_e32 v184, v59, v131
	v_bfe_u32 v188, v184, 16, 1
	v_add3_u32 v184, v184, v188, s81
	ds_write_b16_d16_hi v190, v184 offset:400
	v_mul_f32_e32 v185, v61, v131
	v_bfe_u32 v189, v185, 16, 1
	v_add3_u32 v185, v185, v189, s81
	ds_write_b16_d16_hi v190, v185 offset:464
	v_mul_f32_e32 v182, v52, v132
	v_bfe_u32 v186, v182, 16, 1
	v_add3_u32 v182, v182, v186, s81
	ds_write_b16_d16_hi v190, v182 offset:544
	v_mul_f32_e32 v183, v54, v132
	v_bfe_u32 v187, v183, 16, 1
	v_add3_u32 v183, v183, v187, s81
	ds_write_b16_d16_hi v190, v183 offset:608
	v_mul_f32_e32 v184, v56, v132
	v_bfe_u32 v188, v184, 16, 1
	v_add3_u32 v184, v184, v188, s81
	ds_write_b16_d16_hi v190, v184 offset:672
	v_mul_f32_e32 v185, v58, v132
	v_bfe_u32 v189, v185, 16, 1
	v_add3_u32 v185, v185, v189, s81
	ds_write_b16_d16_hi v190, v185 offset:736
	v_mul_f32_e32 v182, v47, v133
	v_bfe_u32 v186, v182, 16, 1
	v_add3_u32 v182, v182, v186, s81
	ds_write_b16_d16_hi v190, v182 offset:816
	v_mul_f32_e32 v183, v49, v133
	v_bfe_u32 v187, v183, 16, 1
	v_add3_u32 v183, v183, v187, s81
	ds_write_b16_d16_hi v190, v183 offset:880
	v_mul_f32_e32 v184, v51, v133
	v_bfe_u32 v188, v184, 16, 1
	v_add3_u32 v184, v184, v188, s81
	ds_write_b16_d16_hi v190, v184 offset:944
	v_mul_f32_e32 v185, v53, v133
	v_bfe_u32 v189, v185, 16, 1
	v_add3_u32 v185, v185, v189, s81
	ds_write_b16_d16_hi v190, v185 offset:1008
	v_mul_f32_e32 v182, v44, v134
	v_bfe_u32 v186, v182, 16, 1
	v_add3_u32 v182, v182, v186, s81
	ds_write_b16_d16_hi v190, v182 offset:2176
	v_mul_f32_e32 v183, v46, v134
	v_bfe_u32 v187, v183, 16, 1
	v_add3_u32 v183, v183, v187, s81
	ds_write_b16_d16_hi v190, v183 offset:2240
	v_mul_f32_e32 v184, v48, v134
	v_bfe_u32 v188, v184, 16, 1
	v_add3_u32 v184, v184, v188, s81
	ds_write_b16_d16_hi v190, v184 offset:2304
	v_mul_f32_e32 v185, v50, v134
	v_bfe_u32 v189, v185, 16, 1
	v_add3_u32 v185, v185, v189, s81
	ds_write_b16_d16_hi v190, v185 offset:2368
	v_mul_f32_e32 v182, v39, v135
	v_bfe_u32 v186, v182, 16, 1
	v_add3_u32 v182, v182, v186, s81
	ds_write_b16_d16_hi v190, v182 offset:2448
	v_mul_f32_e32 v183, v41, v135
	v_bfe_u32 v187, v183, 16, 1
	v_add3_u32 v183, v183, v187, s81
	ds_write_b16_d16_hi v190, v183 offset:2512
	v_mul_f32_e32 v184, v43, v135
	v_bfe_u32 v188, v184, 16, 1
	v_add3_u32 v184, v184, v188, s81
	ds_write_b16_d16_hi v190, v184 offset:2576
	v_mul_f32_e32 v185, v45, v135
	v_bfe_u32 v189, v185, 16, 1
	v_add3_u32 v185, v185, v189, s81
	ds_write_b16_d16_hi v190, v185 offset:2640
	v_mul_f32_e32 v182, v36, v136
	v_bfe_u32 v186, v182, 16, 1
	v_add3_u32 v182, v182, v186, s81
	ds_write_b16_d16_hi v190, v182 offset:2720
	v_mul_f32_e32 v183, v38, v136
	v_bfe_u32 v187, v183, 16, 1
	v_add3_u32 v183, v183, v187, s81
	ds_write_b16_d16_hi v190, v183 offset:2784
	v_mul_f32_e32 v184, v40, v136
	v_bfe_u32 v188, v184, 16, 1
	v_add3_u32 v184, v184, v188, s81
	ds_write_b16_d16_hi v190, v184 offset:2848
	v_mul_f32_e32 v185, v42, v136
	v_bfe_u32 v189, v185, 16, 1
	v_add3_u32 v185, v185, v189, s81
	ds_write_b16_d16_hi v190, v185 offset:2912
	v_mul_f32_e32 v182, v31, v137
	v_bfe_u32 v186, v182, 16, 1
	v_add3_u32 v182, v182, v186, s81
	ds_write_b16_d16_hi v190, v182 offset:2992
	v_mul_f32_e32 v183, v34, v137
	v_bfe_u32 v187, v183, 16, 1
	v_add3_u32 v183, v183, v187, s81
	ds_write_b16_d16_hi v190, v183 offset:3056
	v_mul_f32_e32 v184, v35, v137
	v_bfe_u32 v188, v184, 16, 1
	v_add3_u32 v184, v184, v188, s81
	ds_write_b16_d16_hi v190, v184 offset:3120
	v_mul_f32_e32 v185, v37, v137
	v_bfe_u32 v189, v185, 16, 1
	v_add3_u32 v185, v185, v189, s81
	ds_write_b16_d16_hi v190, v185 offset:3184
	v_mul_f32_e32 v182, v28, v138
	v_bfe_u32 v186, v182, 16, 1
	v_add3_u32 v182, v182, v186, s81
	ds_write_b16_d16_hi v190, v182 offset:4352
	v_mul_f32_e32 v183, v30, v138
	v_bfe_u32 v187, v183, 16, 1
	v_add3_u32 v183, v183, v187, s81
	ds_write_b16_d16_hi v190, v183 offset:4416
	v_mul_f32_e32 v184, v32, v138
	v_bfe_u32 v188, v184, 16, 1
	v_add3_u32 v184, v184, v188, s81
	ds_write_b16_d16_hi v190, v184 offset:4480
	v_mul_f32_e32 v185, v33, v138
	v_bfe_u32 v189, v185, 16, 1
	v_add3_u32 v185, v185, v189, s81
	ds_write_b16_d16_hi v190, v185 offset:4544
	v_mul_f32_e32 v182, v23, v139
	v_bfe_u32 v186, v182, 16, 1
	v_add3_u32 v182, v182, v186, s81
	ds_write_b16_d16_hi v190, v182 offset:4624
	v_mul_f32_e32 v183, v26, v139
	v_bfe_u32 v187, v183, 16, 1
	v_add3_u32 v183, v183, v187, s81
	ds_write_b16_d16_hi v190, v183 offset:4688
	v_mul_f32_e32 v184, v27, v139
	v_bfe_u32 v188, v184, 16, 1
	v_add3_u32 v184, v184, v188, s81
	ds_write_b16_d16_hi v190, v184 offset:4752
	v_mul_f32_e32 v185, v29, v139
	v_bfe_u32 v189, v185, 16, 1
	v_add3_u32 v185, v185, v189, s81
	ds_write_b16_d16_hi v190, v185 offset:4816
	v_mul_f32_e32 v182, v20, v140
	v_bfe_u32 v186, v182, 16, 1
	v_add3_u32 v182, v182, v186, s81
	ds_write_b16_d16_hi v190, v182 offset:4896
	v_mul_f32_e32 v183, v22, v140
	v_bfe_u32 v187, v183, 16, 1
	v_add3_u32 v183, v183, v187, s81
	ds_write_b16_d16_hi v190, v183 offset:4960
	v_mul_f32_e32 v184, v24, v140
	v_bfe_u32 v188, v184, 16, 1
	v_add3_u32 v184, v184, v188, s81
	ds_write_b16_d16_hi v190, v184 offset:5024
	v_mul_f32_e32 v185, v25, v140
	v_bfe_u32 v189, v185, 16, 1
	v_add3_u32 v185, v185, v189, s81
	ds_write_b16_d16_hi v190, v185 offset:5088
	v_mul_f32_e32 v182, v15, v141
	v_bfe_u32 v186, v182, 16, 1
	v_add3_u32 v182, v182, v186, s81
	ds_write_b16_d16_hi v190, v182 offset:5168
	v_mul_f32_e32 v183, v18, v141
	v_bfe_u32 v187, v183, 16, 1
	v_add3_u32 v183, v183, v187, s81
	ds_write_b16_d16_hi v190, v183 offset:5232
	v_mul_f32_e32 v184, v19, v141
	v_bfe_u32 v188, v184, 16, 1
	v_add3_u32 v184, v184, v188, s81
	ds_write_b16_d16_hi v190, v184 offset:5296
	v_mul_f32_e32 v185, v21, v141
	v_bfe_u32 v189, v185, 16, 1
	v_add3_u32 v185, v185, v189, s81
	ds_write_b16_d16_hi v190, v185 offset:5360
	v_mul_f32_e32 v182, v12, v142
	v_bfe_u32 v186, v182, 16, 1
	v_add3_u32 v182, v182, v186, s81
	ds_write_b16_d16_hi v190, v182 offset:6528
	v_mul_f32_e32 v183, v14, v142
	v_bfe_u32 v187, v183, 16, 1
	v_add3_u32 v183, v183, v187, s81
	ds_write_b16_d16_hi v190, v183 offset:6592
	v_mul_f32_e32 v184, v16, v142
	v_bfe_u32 v188, v184, 16, 1
	v_add3_u32 v184, v184, v188, s81
	ds_write_b16_d16_hi v190, v184 offset:6656
	v_mul_f32_e32 v185, v17, v142
	v_bfe_u32 v189, v185, 16, 1
	v_add3_u32 v185, v185, v189, s81
	ds_write_b16_d16_hi v190, v185 offset:6720
	v_mul_f32_e32 v182, v6, v143
	v_bfe_u32 v186, v182, 16, 1
	v_add3_u32 v182, v182, v186, s81
	ds_write_b16_d16_hi v190, v182 offset:6800
	v_mul_f32_e32 v183, v10, v143
	v_bfe_u32 v187, v183, 16, 1
	v_add3_u32 v183, v183, v187, s81
	ds_write_b16_d16_hi v190, v183 offset:6864
	v_mul_f32_e32 v184, v11, v143
	v_bfe_u32 v188, v184, 16, 1
	v_add3_u32 v184, v184, v188, s81
	ds_write_b16_d16_hi v190, v184 offset:6928
	v_mul_f32_e32 v185, v13, v143
	v_bfe_u32 v189, v185, 16, 1
	v_add3_u32 v185, v185, v189, s81
	ds_write_b16_d16_hi v190, v185 offset:6992
	v_mul_f32_e32 v182, v3, v144
	v_bfe_u32 v186, v182, 16, 1
	v_add3_u32 v182, v182, v186, s81
	ds_write_b16_d16_hi v190, v182 offset:7072
	v_mul_f32_e32 v183, v5, v144
	v_bfe_u32 v187, v183, 16, 1
	v_add3_u32 v183, v183, v187, s81
	ds_write_b16_d16_hi v190, v183 offset:7136
	v_mul_f32_e32 v184, v7, v144
	v_bfe_u32 v188, v184, 16, 1
	v_add3_u32 v184, v184, v188, s81
	ds_write_b16_d16_hi v190, v184 offset:7200
	v_mul_f32_e32 v185, v9, v144
	v_bfe_u32 v189, v185, 16, 1
	v_add3_u32 v185, v185, v189, s81
	ds_write_b16_d16_hi v190, v185 offset:7264
	v_mul_f32_e32 v182, v0, v145
	v_bfe_u32 v186, v182, 16, 1
	v_add3_u32 v182, v182, v186, s81
	ds_write_b16_d16_hi v190, v182 offset:7344
	v_mul_f32_e32 v183, v1, v145
	v_bfe_u32 v187, v183, 16, 1
	v_add3_u32 v183, v183, v187, s81
	ds_write_b16_d16_hi v190, v183 offset:7408
	v_mul_f32_e32 v184, v2, v145
	v_bfe_u32 v188, v184, 16, 1
	v_add3_u32 v184, v184, v188, s81
	ds_write_b16_d16_hi v190, v184 offset:7472
	v_mul_f32_e32 v185, v4, v145
	v_bfe_u32 v189, v185, 16, 1
	v_add3_u32 v185, v185, v189, s81
	ds_write_b16_d16_hi v190, v185 offset:7536
	s_or_b32 s0, s40, s99
	s_mov_b32 s1, s41
	s_lshl_b64 s[0:1], s[0:1], 11
	v_lshlrev_b32_e32 v0, 1, v169
	v_lshrrev_b32_e32 v6, 4, v168
	v_and_b32_e32 v96, 0xf0, v0
	v_mul_u32_u24_e32 v0, 0x110, v6
	s_add_u32 s0, s92, s0
	v_add3_u32 v8, s34, v96, v0
	s_addc_u32 s1, s93, s1
	s_lshl_b32 s35, s98, 8
	s_add_u32 s0, s0, s35
	s_addc_u32 s1, s1, 0
	s_waitcnt lgkmcnt(0)
	ds_read_b128 v[132:135], v8
	ds_read_b128 v[136:139], v8 offset:1088
	ds_read_b128 v[140:143], v8 offset:2176
	ds_read_b128 v[144:147], v8 offset:3264
	ds_read_b128 v[148:151], v8 offset:4352
	ds_read_b128 v[172:175], v8 offset:5440
	ds_read_b128 v[176:179], v8 offset:6528
	ds_read_b128 v[180:183], v8 offset:7616
	v_lshl_add_u64 v[4:5], s[0:1], 0, v[96:97]
	v_lshlrev_b32_e32 v96, 11, v6
	v_lshl_add_u64 v[6:7], v[4:5], 0, v[96:97]
	s_waitcnt lgkmcnt(7)
	global_store_dwordx4 v[6:7], v[132:135], off sc0 sc1
	v_or_b32_e32 v6, 0x2000, v96
	v_mov_b32_e32 v7, v97
	v_lshl_add_u64 v[6:7], v[4:5], 0, v[6:7]
	s_waitcnt lgkmcnt(6)
	global_store_dwordx4 v[6:7], v[136:139], off sc0 sc1
	v_or_b32_e32 v6, 0x4000, v96
	v_mov_b32_e32 v7, v97
	v_lshl_add_u64 v[6:7], v[4:5], 0, v[6:7]
	s_waitcnt lgkmcnt(5)
	global_store_dwordx4 v[6:7], v[140:143], off sc0 sc1
	v_or_b32_e32 v6, 0x6000, v96
	v_mov_b32_e32 v7, v97
	v_lshl_add_u64 v[6:7], v[4:5], 0, v[6:7]
	s_waitcnt lgkmcnt(4)
	global_store_dwordx4 v[6:7], v[144:147], off sc0 sc1
	v_or_b32_e32 v6, 0x8000, v96
	v_mov_b32_e32 v7, v97
	v_lshl_add_u64 v[6:7], v[4:5], 0, v[6:7]
	s_waitcnt lgkmcnt(3)
	global_store_dwordx4 v[6:7], v[148:151], off sc0 sc1
	v_or_b32_e32 v6, 0xa000, v96
	v_mov_b32_e32 v7, v97
	v_lshl_add_u64 v[6:7], v[4:5], 0, v[6:7]
	s_waitcnt lgkmcnt(2)
	global_store_dwordx4 v[6:7], v[172:175], off sc0 sc1
	v_or_b32_e32 v6, 0xc000, v96
	v_mov_b32_e32 v7, v97
	v_lshl_add_u64 v[6:7], v[4:5], 0, v[6:7]
	s_waitcnt lgkmcnt(1)
	global_store_dwordx4 v[6:7], v[176:179], off sc0 sc1
	v_or_b32_e32 v96, 0xe000, v96
	v_lshl_add_u64 v[4:5], v[4:5], 0, v[96:97]
	s_waitcnt lgkmcnt(0)
	global_store_dwordx4 v[4:5], v[180:183], off sc0 sc1
	s_branch .LBB0_275
